# MoBA loop: LDS-DMA addresses as SGPR tile base + precomputed per-lane offsets (no 64-bit VALU adds per pair); instance B reuses instance A's fragment addresses; l update folded
# speedup vs baseline: 1.0151x; 1.0001x over previous
.LBB0_66:
	s_or_b64 exec, exec, s[30:31]
	v_subrev_u32_e32 v64, s33, v134
	v_add_u32_e32 v137, v64, v136
	v_add_u32_e32 v139, v64, v138
	v_add_u32_e32 v136, v136, v96
	v_add_u32_e32 v138, v138, v132
	s_lshl_b32 s4, s4, 2
	s_movk_i32 s6, 0xff40
	s_mov_b32 s10, 2
	s_add_i32 s4, s4, 4
	v_subrev_u32_e32 v167, 63, v140
	v_add3_u32 v164, v140, v164, s6
	s_addk_i32 s5, 0x80
	s_mov_b32 s6, 0
	s_mov_b32 s7, 0x10000
.LBB0_67:
	s_waitcnt vmcnt(0)
	s_add_i32 s8, s10, 2
	s_and_b32 s9, s7, 0x10000
	s_cmp_ge_u32 s8, s4
	s_barrier
	s_cbranch_scc1 .LBB0_69
	s_add_i32 s13, s6, 0x100
	s_and_b32 s12, s6, 0xffffff00
	s_and_b32 s13, s13, 0x80
	s_or_b32 s12, s12, s13
	s_xor_b32 s11, s9, 0x10000
	s_ashr_i32 s13, s12, 31
	s_add_i32 s11, s11, 0
	s_lshl_b64 s[12:13], s[12:13], 11
	s_add_u32 s14, s33, s12
	s_addc_u32 s15, s74, s13
	s_add_i32 s12, s11, 0x4000
	s_add_i32 s13, s75, s11
	s_mov_b32 s16, m0
	s_mov_b32 m0, s13
	s_nop 0
	global_load_lds_dwordx4 v136, s[14:15]
	s_mov_b32 m0, s16
	s_add_i32 s13, s12, s75
	s_mov_b32 s16, m0
	s_mov_b32 m0, s13
	s_nop 0
	global_load_lds_dwordx4 v137, s[14:15]
	s_mov_b32 m0, s16
	s_add_i32 s13, s76, s11
	s_mov_b32 s16, m0
	s_mov_b32 m0, s13
	s_nop 0
	global_load_lds_dwordx4 v138, s[14:15]
	s_mov_b32 m0, s16
	s_add_i32 s12, s12, s76
	s_mov_b32 s13, m0
	s_mov_b32 m0, s12
	s_nop 0
	global_load_lds_dwordx4 v139, s[14:15]
	s_mov_b32 m0, s13
	s_add_i32 s12, s6, 64
	s_add_i32 s13, s6, 0x140
	s_and_b32 s12, s12, 0xffffff00
	s_and_b32 s13, s13, 0xc0
	s_or_b32 s68, s13, s12
	s_add_i32 s16, s11, 0x8000
	s_lshl_b64 s[12:13], s[68:69], 11
	s_add_u32 s14, s33, s12
	s_addc_u32 s15, s74, s13
	s_add_i32 s11, s11, 0xc000
	s_add_i32 s12, s75, s16
	s_mov_b32 s13, m0
	s_mov_b32 m0, s12
	s_nop 0
	global_load_lds_dwordx4 v136, s[14:15]
	s_mov_b32 m0, s13
	s_add_i32 s12, s11, s75
	s_mov_b32 s13, m0
	s_mov_b32 m0, s12
	s_nop 0
	global_load_lds_dwordx4 v137, s[14:15]
	s_mov_b32 m0, s13
	s_add_i32 s12, s76, s16
	s_mov_b32 s13, m0
	s_mov_b32 m0, s12
	s_nop 0
	global_load_lds_dwordx4 v138, s[14:15]
	s_mov_b32 m0, s13
	s_add_i32 s11, s11, s76
	s_mov_b32 s12, m0
	s_mov_b32 m0, s11
	s_nop 0
	global_load_lds_dwordx4 v139, s[14:15]
	s_mov_b32 m0, s12

.LBB0_74:
	v_add_u32_e32 v169, s9, v148
	v_add_u32_e32 v183, v169, v149
	v_add_u32_e32 v184, v169, v150
	v_add_u32_e32 v185, v169, v151
	v_add_u32_e32 v186, v169, v152
	ds_read_b128 v[170:173], v183
	ds_read_b128 v[174:177], v183 offset:8192
	ds_read_b128 v[178:181], v184
	ds_read_b128 v[188:191], v184 offset:8192
	ds_read_b128 v[192:195], v185
	ds_read_b128 v[198:201], v185 offset:8192
	ds_read_b128 v[202:205], v186
	s_add_i32 s10, s6, 0x80
	v_cmp_gt_i32_e32 vcc, s10, v167
	s_and_b64 s[10:11], s[36:37], vcc
	v_cmp_lt_i32_e64 s[40:41], -1, v140
	v_xor_b32_e32 v223, 0x80000000, v142
	s_nop 0
	v_cndmask_b32_e64 v222, v235, v223, s[40:41]
	v_cndmask_b32_e64 v222, v222, v223, s[36:37]
	v_mov_b32_e32 v206, v222
	v_mov_b32_e32 v207, v222
	v_mov_b32_e32 v208, v222
	v_mov_b32_e32 v209, v222
	v_mov_b32_e32 v210, v222
	v_mov_b32_e32 v211, v222
	v_mov_b32_e32 v212, v222
	v_mov_b32_e32 v213, v222
	v_mov_b32_e32 v214, v222
	v_mov_b32_e32 v215, v222
	v_mov_b32_e32 v216, v222
	v_mov_b32_e32 v217, v222
	v_mov_b32_e32 v218, v222
	v_mov_b32_e32 v219, v222
	v_mov_b32_e32 v220, v222
	v_mov_b32_e32 v221, v222
	v_add_u32_e32 v187, v169, v153
	v_add_u32_e32 v222, v169, v154
	v_add_u32_e32 v223, v169, v155
	v_add_u32_e32 v169, v169, v156
	s_waitcnt lgkmcnt(6)
	v_mfma_f32_32x32x16_bf16 v[80:95], v[170:173], v[98:101], v[206:221]
	ds_read_b128 v[170:173], v186 offset:8192
	v_add_u32_e32 v96, s9, v159
	v_add3_u32 v96, v96, v160, v157
	v_add_u32_e32 v132, v96, v161
	v_add_u32_e32 v134, v96, v162
	v_add_u32_e32 v135, v96, v163
	v_add_u32_e32 v96, v96, v158
	s_waitcnt lgkmcnt(6)
	v_mfma_f32_32x32x16_bf16 v[64:79], v[174:177], v[98:101], v[206:221]
	ds_read_b128 v[174:177], v187
	s_waitcnt lgkmcnt(6)
	v_mfma_f32_32x32x16_bf16 v[80:95], v[178:181], v[102:105], v[80:95]
	ds_read_b128 v[178:181], v187 offset:8192
	s_waitcnt lgkmcnt(6)
	v_mfma_f32_32x32x16_bf16 v[64:79], v[188:191], v[102:105], v[64:79]
	ds_read_b128 v[188:191], v222
	s_waitcnt lgkmcnt(6)
	v_mfma_f32_32x32x16_bf16 v[80:95], v[192:195], v[106:109], v[80:95]
	ds_read_b128 v[192:195], v222 offset:8192
	s_waitcnt lgkmcnt(6)
	v_mfma_f32_32x32x16_bf16 v[64:79], v[198:201], v[106:109], v[64:79]
	ds_read_b128 v[198:201], v223
	s_waitcnt lgkmcnt(6)
	v_mfma_f32_32x32x16_bf16 v[80:95], v[202:205], v[110:113], v[80:95]
	ds_read_b128 v[202:205], v223 offset:8192
	s_waitcnt lgkmcnt(6)
	v_mfma_f32_32x32x16_bf16 v[64:79], v[170:173], v[110:113], v[64:79]
	ds_read_b128 v[170:173], v169
	s_waitcnt lgkmcnt(6)
	v_mfma_f32_32x32x16_bf16 v[80:95], v[174:177], v[114:117], v[80:95]
	ds_read_b128 v[174:177], v169 offset:8192
	s_waitcnt lgkmcnt(6)
	v_mfma_f32_32x32x16_bf16 v[64:79], v[178:181], v[114:117], v[64:79]
	s_waitcnt lgkmcnt(5)
	v_mfma_f32_32x32x16_bf16 v[80:95], v[188:191], v[118:121], v[80:95]
	ds_read_b64_tr_b16 v[188:189], v96 offset:16384
	ds_read_b64_tr_b16 v[190:191], v96 offset:18432
	s_waitcnt lgkmcnt(6)
	v_mfma_f32_32x32x16_bf16 v[64:79], v[192:195], v[118:121], v[64:79]
	ds_read_b64_tr_b16 v[192:193], v132 offset:16384
	ds_read_b64_tr_b16 v[194:195], v132 offset:18432
	s_waitcnt lgkmcnt(7)
	v_mfma_f32_32x32x16_bf16 v[80:95], v[198:201], v[122:125], v[80:95]
	ds_read_b64_tr_b16 v[198:199], v134 offset:16384
	ds_read_b64_tr_b16 v[200:201], v134 offset:18432
	s_waitcnt lgkmcnt(8)
	v_mfma_f32_32x32x16_bf16 v[64:79], v[202:205], v[122:125], v[64:79]
	ds_read_b64_tr_b16 v[202:203], v135 offset:16384
	ds_read_b64_tr_b16 v[204:205], v135 offset:18432
	s_waitcnt lgkmcnt(9)
	v_mfma_f32_32x32x16_bf16 v[80:95], v[170:173], v[126:129], v[80:95]
	s_waitcnt lgkmcnt(8)
	v_mfma_f32_32x32x16_bf16 v[64:79], v[174:177], v[126:129], v[64:79]
	s_and_saveexec_b64 s[40:41], s[10:11]
	s_cbranch_execz .LBB0_76
	v_sub_u32_e32 v169, v140, v146
	v_cmp_lt_i32_e32 vcc, -1, v169
	s_nop 4
	v_cndmask_b32_e32 v80, v235, v80, vcc
	v_cmp_lt_i32_e32 vcc, 0, v169
	s_nop 1
	v_cndmask_b32_e32 v81, v235, v81, vcc
	v_cmp_lt_i32_e32 vcc, 1, v169
	s_nop 1
	v_cndmask_b32_e32 v82, v235, v82, vcc
	v_cmp_lt_i32_e32 vcc, 2, v169
	s_nop 1
	v_cndmask_b32_e32 v83, v235, v83, vcc
	v_cmp_lt_i32_e32 vcc, 7, v169
	s_nop 1
	v_cndmask_b32_e32 v84, v235, v84, vcc
	v_cmp_lt_i32_e32 vcc, 8, v169
	s_nop 1
	v_cndmask_b32_e32 v85, v235, v85, vcc
	v_cmp_lt_i32_e32 vcc, 9, v169
	s_nop 1
	v_cndmask_b32_e32 v86, v235, v86, vcc
	v_cmp_lt_i32_e32 vcc, 10, v169
	s_nop 1
	v_cndmask_b32_e32 v87, v235, v87, vcc
	v_cmp_lt_i32_e32 vcc, 15, v169
	s_nop 1
	v_cndmask_b32_e32 v88, v235, v88, vcc
	v_cmp_lt_i32_e32 vcc, 16, v169
	s_nop 1
	v_cndmask_b32_e32 v89, v235, v89, vcc
	v_cmp_lt_i32_e32 vcc, 17, v169
	s_nop 1
	v_cndmask_b32_e32 v90, v235, v90, vcc
	v_cmp_lt_i32_e32 vcc, 18, v169
	s_nop 1
	v_cndmask_b32_e32 v91, v235, v91, vcc
	v_cmp_lt_i32_e32 vcc, 23, v169
	s_nop 1
	v_cndmask_b32_e32 v92, v235, v92, vcc
	v_cmp_lt_i32_e32 vcc, 24, v169
	s_nop 1
	v_cndmask_b32_e32 v93, v235, v93, vcc
	v_cmp_lt_i32_e32 vcc, 25, v169
	s_nop 1
	v_cndmask_b32_e32 v94, v235, v94, vcc
	v_cmp_lt_i32_e32 vcc, 26, v169
	s_nop 1
	v_cndmask_b32_e32 v95, v235, v95, vcc
	v_cmp_lt_i32_e32 vcc, 31, v169
	s_nop 1
	v_cndmask_b32_e32 v64, v235, v64, vcc
	v_cmp_lt_i32_e32 vcc, 32, v169
	s_nop 1
	v_cndmask_b32_e32 v65, v235, v65, vcc
	v_cmp_lt_i32_e32 vcc, 33, v169
	s_nop 1
	v_cndmask_b32_e32 v66, v235, v66, vcc
	v_cmp_lt_i32_e32 vcc, 34, v169
	s_nop 1
	v_cndmask_b32_e32 v67, v235, v67, vcc
	v_cmp_lt_i32_e32 vcc, 39, v169
	s_nop 1
	v_cndmask_b32_e32 v68, v235, v68, vcc
	v_cmp_lt_i32_e32 vcc, 40, v169
	s_nop 1
	v_cndmask_b32_e32 v69, v235, v69, vcc
	v_cmp_lt_i32_e32 vcc, 41, v169
	s_nop 1
	v_cndmask_b32_e32 v70, v235, v70, vcc
	v_cmp_lt_i32_e32 vcc, 42, v169
	s_nop 1
	v_cndmask_b32_e32 v71, v235, v71, vcc
	v_cmp_lt_i32_e32 vcc, 47, v169
	s_nop 1
	v_cndmask_b32_e32 v72, v235, v72, vcc
	v_cmp_lt_i32_e32 vcc, 48, v169
	s_nop 1
	v_cndmask_b32_e32 v73, v235, v73, vcc
	v_cmp_lt_i32_e32 vcc, 49, v169
	s_nop 1
	v_cndmask_b32_e32 v74, v235, v74, vcc
	v_cmp_lt_i32_e32 vcc, 50, v169
	s_nop 1
	v_cndmask_b32_e32 v75, v235, v75, vcc
	v_cmp_lt_i32_e32 vcc, 55, v169
	s_nop 1
	v_cndmask_b32_e32 v76, v235, v76, vcc
	v_cmp_lt_i32_e32 vcc, 56, v169
	s_nop 1
	v_cndmask_b32_e32 v77, v235, v77, vcc
	v_cmp_lt_i32_e32 vcc, 57, v169
	s_nop 1
	v_cndmask_b32_e32 v78, v235, v78, vcc
	v_cmp_lt_i32_e32 vcc, 58, v169
	s_nop 1
	v_cndmask_b32_e32 v79, v235, v79, vcc

.LBB0_78:
	v_exp_f32_e32 v171, v80
	v_exp_f32_e32 v81, v81
	v_exp_f32_e32 v173, v69
	v_exp_f32_e32 v82, v82
	v_exp_f32_e32 v174, v70
	v_exp_f32_e32 v83, v83
	v_exp_f32_e32 v71, v71
	v_add_f32_e32 v80, 0, v171
	v_exp_f32_e32 v84, v84
	v_exp_f32_e32 v175, v72
	v_add_f32_e32 v80, v81, v80
	v_exp_f32_e32 v85, v85
	v_exp_f32_e32 v176, v73
	v_add_f32_e32 v80, v82, v80
	v_exp_f32_e32 v86, v86
	v_exp_f32_e32 v87, v87
	v_exp_f32_e32 v177, v74
	v_add_f32_e32 v80, v83, v80
	v_exp_f32_e32 v178, v75
	v_add_f32_e32 v80, v84, v80
	v_exp_f32_e32 v179, v76
	v_cvt_pk_bf16_f32 v76, v171, v81
	v_add_f32_e32 v80, v85, v80
	v_exp_f32_e32 v180, v77
	v_add_f32_e32 v80, v86, v80
	v_exp_f32_e32 v181, v78
	v_mov_b32_e32 v69, v79
	v_cvt_pk_bf16_f32 v79, v86, v87
	v_cvt_pk_bf16_f32 v77, v82, v83
	v_cvt_pk_bf16_f32 v78, v84, v85
	v_add_f32_e32 v80, v87, v80
	v_exp_f32_e32 v88, v88
	v_exp_f32_e32 v89, v89
	s_waitcnt lgkmcnt(6)
	v_mfma_f32_32x32x16_bf16 v[48:63], v[188:191], v[76:79], v[48:63]
	ds_read_b64_tr_b16 v[188:189], v96 offset:20480
	ds_read_b64_tr_b16 v[190:191], v96 offset:22528
	v_add_f32_e32 v80, v88, v80
	v_cvt_pk_bf16_f32 v72, v88, v89
	v_exp_f32_e32 v90, v90
	s_waitcnt lgkmcnt(6)
	v_mfma_f32_32x32x16_bf16 v[32:47], v[192:195], v[76:79], v[32:47]
	ds_read_b64_tr_b16 v[192:193], v132 offset:20480
	ds_read_b64_tr_b16 v[194:195], v132 offset:22528
	v_exp_f32_e32 v91, v91
	s_waitcnt lgkmcnt(6)
	v_mfma_f32_32x32x16_bf16 v[16:31], v[198:201], v[76:79], v[16:31]
	ds_read_b64_tr_b16 v[198:199], v134 offset:20480
	ds_read_b64_tr_b16 v[200:201], v134 offset:22528
	v_exp_f32_e32 v92, v92
	v_exp_f32_e32 v93, v93
	v_exp_f32_e32 v94, v94
	v_exp_f32_e32 v95, v95
	v_add_f32_e32 v80, v89, v80
	v_add_f32_e32 v80, v90, v80
	s_waitcnt lgkmcnt(6)
	v_mfma_f32_32x32x16_bf16 v[0:15], v[202:205], v[76:79], v[0:15]
	ds_read_b64_tr_b16 v[202:203], v135 offset:20480
	ds_read_b64_tr_b16 v[204:205], v135 offset:22528
	v_add_f32_e32 v80, v91, v80
	v_cvt_pk_bf16_f32 v73, v90, v91
	v_cvt_pk_bf16_f32 v74, v92, v93
	v_cvt_pk_bf16_f32 v75, v94, v95
	v_add_f32_e32 v80, v92, v80
	v_exp_f32_e32 v64, v64
	s_waitcnt lgkmcnt(6)
	v_mfma_f32_32x32x16_bf16 v[48:63], v[188:191], v[72:75], v[48:63]
	ds_read_b64_tr_b16 v[188:189], v96 offset:24576
	ds_read_b64_tr_b16 v[190:191], v96 offset:26624
	v_add_f32_e32 v80, v93, v80
	v_exp_f32_e32 v65, v65
	v_add_f32_e32 v80, v94, v80
	v_exp_f32_e32 v66, v66
	v_add_f32_e32 v80, v95, v80
	v_exp_f32_e32 v67, v67
	v_add_f32_e32 v80, v64, v80
	v_exp_f32_e32 v172, v68
	v_add_f32_e32 v80, v65, v80
	s_waitcnt lgkmcnt(6)
	v_mfma_f32_32x32x16_bf16 v[32:47], v[192:195], v[72:75], v[32:47]
	ds_read_b64_tr_b16 v[192:193], v132 offset:24576
	ds_read_b64_tr_b16 v[194:195], v132 offset:26624
	v_add_f32_e32 v80, v66, v80
	v_add_f32_e32 v80, v67, v80
	v_add_f32_e32 v68, v172, v80
	v_add_f32_e32 v68, v173, v68
	v_add_f32_e32 v68, v174, v68
	v_add_f32_e32 v68, v71, v68
	s_waitcnt lgkmcnt(6)
	v_mfma_f32_32x32x16_bf16 v[16:31], v[198:201], v[72:75], v[16:31]
	ds_read_b64_tr_b16 v[198:199], v134 offset:24576
	ds_read_b64_tr_b16 v[200:201], v134 offset:26624
	v_add_f32_e32 v68, v175, v68
	v_add_f32_e32 v68, v176, v68
	v_add_f32_e32 v68, v177, v68
	v_add_f32_e32 v68, v178, v68
	v_exp_f32_e32 v182, v69
	v_add_f32_e32 v68, v179, v68
	s_waitcnt lgkmcnt(6)
	v_mfma_f32_32x32x16_bf16 v[0:15], v[202:205], v[72:75], v[0:15]
	ds_read_b64_tr_b16 v[202:203], v135 offset:24576
	ds_read_b64_tr_b16 v[204:205], v135 offset:26624
	v_add_f32_e32 v68, v180, v68
	v_add_f32_e32 v68, v181, v68
	v_add_f32_e32 v80, v182, v68
	v_cvt_pk_bf16_f32 v68, v64, v65
	v_cvt_pk_bf16_f32 v69, v66, v67
	v_cvt_pk_bf16_f32 v70, v172, v173
	v_cvt_pk_bf16_f32 v71, v174, v71
	v_cvt_pk_bf16_f32 v64, v175, v176
	v_cvt_pk_bf16_f32 v65, v177, v178
	s_waitcnt lgkmcnt(6)
	v_mfma_f32_32x32x16_bf16 v[48:63], v[188:191], v[68:71], v[48:63]
	ds_read_b64_tr_b16 v[188:189], v96 offset:28672
	ds_read_b64_tr_b16 v[190:191], v96 offset:30720
	v_cvt_pk_bf16_f32 v66, v179, v180
	v_cvt_pk_bf16_f32 v67, v181, v182
	v_add_f32_e32 v168, v168, v80
	s_waitcnt lgkmcnt(6)
	v_mfma_f32_32x32x16_bf16 v[32:47], v[192:195], v[68:71], v[32:47]
	ds_read_b64_tr_b16 v[192:193], v132 offset:28672
	ds_read_b64_tr_b16 v[194:195], v132 offset:30720
	s_waitcnt lgkmcnt(6)
	v_mfma_f32_32x32x16_bf16 v[16:31], v[198:201], v[68:71], v[16:31]
	ds_read_b64_tr_b16 v[198:199], v134 offset:28672
	ds_read_b64_tr_b16 v[200:201], v134 offset:30720
	s_waitcnt lgkmcnt(6)
	v_mfma_f32_32x32x16_bf16 v[0:15], v[202:205], v[68:71], v[0:15]
	ds_read_b64_tr_b16 v[202:203], v135 offset:28672
	ds_read_b64_tr_b16 v[204:205], v135 offset:30720
	s_waitcnt lgkmcnt(6)
	v_mfma_f32_32x32x16_bf16 v[48:63], v[188:191], v[64:67], v[48:63]
	s_waitcnt lgkmcnt(4)
	v_mfma_f32_32x32x16_bf16 v[32:47], v[192:195], v[64:67], v[32:47]
	s_waitcnt lgkmcnt(2)
	v_mfma_f32_32x32x16_bf16 v[16:31], v[198:201], v[64:67], v[16:31]
	s_waitcnt lgkmcnt(0)
	v_mfma_f32_32x32x16_bf16 v[0:15], v[202:205], v[64:67], v[0:15]

.LBB0_84:
	ds_read_b128 v[170:173], v183 offset:32768
	ds_read_b128 v[174:177], v183 offset:40960
	ds_read_b128 v[178:181], v184 offset:32768
	ds_read_b128 v[188:191], v184 offset:40960
	ds_read_b128 v[192:195], v185 offset:32768
	ds_read_b128 v[198:201], v185 offset:40960
	ds_read_b128 v[202:205], v186 offset:32768
	s_add_i32 s10, s6, 0xc0
	v_cmp_gt_i32_e32 vcc, s10, v167
	s_and_b64 s[10:11], s[36:37], vcc
	s_waitcnt lgkmcnt(6)
	v_mfma_f32_32x32x16_bf16 v[80:95], v[170:173], v[98:101], v[206:221]
	ds_read_b128 v[170:173], v186 offset:40960
	s_waitcnt lgkmcnt(6)
	v_mfma_f32_32x32x16_bf16 v[64:79], v[174:177], v[98:101], v[206:221]
	ds_read_b128 v[174:177], v187 offset:32768
	s_waitcnt lgkmcnt(6)
	v_mfma_f32_32x32x16_bf16 v[80:95], v[178:181], v[102:105], v[80:95]
	ds_read_b128 v[178:181], v187 offset:40960
	s_waitcnt lgkmcnt(6)
	v_mfma_f32_32x32x16_bf16 v[64:79], v[188:191], v[102:105], v[64:79]
	ds_read_b128 v[188:191], v222 offset:32768
	s_waitcnt lgkmcnt(6)
	v_mfma_f32_32x32x16_bf16 v[80:95], v[192:195], v[106:109], v[80:95]
	ds_read_b128 v[192:195], v222 offset:40960
	s_waitcnt lgkmcnt(6)
	v_mfma_f32_32x32x16_bf16 v[64:79], v[198:201], v[106:109], v[64:79]
	ds_read_b128 v[198:201], v223 offset:32768
	s_waitcnt lgkmcnt(6)
	v_mfma_f32_32x32x16_bf16 v[80:95], v[202:205], v[110:113], v[80:95]
	ds_read_b128 v[202:205], v223 offset:40960
	s_waitcnt lgkmcnt(6)
	v_mfma_f32_32x32x16_bf16 v[64:79], v[170:173], v[110:113], v[64:79]
	ds_read_b128 v[170:173], v169 offset:32768
	s_waitcnt lgkmcnt(6)
	v_mfma_f32_32x32x16_bf16 v[80:95], v[174:177], v[114:117], v[80:95]
	ds_read_b128 v[174:177], v169 offset:40960
	s_waitcnt lgkmcnt(6)
	v_mfma_f32_32x32x16_bf16 v[64:79], v[178:181], v[114:117], v[64:79]
	s_waitcnt lgkmcnt(5)
	v_mfma_f32_32x32x16_bf16 v[80:95], v[188:191], v[118:121], v[80:95]
	ds_read_b64_tr_b16 v[188:189], v96 offset:49152
	ds_read_b64_tr_b16 v[190:191], v96 offset:51200
	s_waitcnt lgkmcnt(6)
	v_mfma_f32_32x32x16_bf16 v[64:79], v[192:195], v[118:121], v[64:79]
	ds_read_b64_tr_b16 v[192:193], v132 offset:49152
	ds_read_b64_tr_b16 v[194:195], v132 offset:51200
	s_waitcnt lgkmcnt(7)
	v_mfma_f32_32x32x16_bf16 v[80:95], v[198:201], v[122:125], v[80:95]
	ds_read_b64_tr_b16 v[198:199], v134 offset:49152
	ds_read_b64_tr_b16 v[200:201], v134 offset:51200
	s_waitcnt lgkmcnt(8)
	v_mfma_f32_32x32x16_bf16 v[64:79], v[202:205], v[122:125], v[64:79]
	ds_read_b64_tr_b16 v[202:203], v135 offset:49152
	ds_read_b64_tr_b16 v[204:205], v135 offset:51200
	s_waitcnt lgkmcnt(9)
	v_mfma_f32_32x32x16_bf16 v[80:95], v[170:173], v[126:129], v[80:95]
	s_waitcnt lgkmcnt(8)
	v_mfma_f32_32x32x16_bf16 v[64:79], v[174:177], v[126:129], v[64:79]
	s_and_saveexec_b64 s[38:39], s[10:11]
	s_cbranch_execz .LBB0_86
	v_sub_u32_e32 v140, v133, v146
	v_cmp_lt_i32_e32 vcc, -1, v140
	s_nop 4
	v_cndmask_b32_e32 v80, v235, v80, vcc
	v_cmp_lt_i32_e32 vcc, 0, v140
	s_nop 1
	v_cndmask_b32_e32 v81, v235, v81, vcc
	v_cmp_lt_i32_e32 vcc, 1, v140
	s_nop 1
	v_cndmask_b32_e32 v82, v235, v82, vcc
	v_cmp_lt_i32_e32 vcc, 2, v140
	s_nop 1
	v_cndmask_b32_e32 v83, v235, v83, vcc
	v_cmp_lt_i32_e32 vcc, 7, v140
	s_nop 1
	v_cndmask_b32_e32 v84, v235, v84, vcc
	v_cmp_lt_i32_e32 vcc, 8, v140
	s_nop 1
	v_cndmask_b32_e32 v85, v235, v85, vcc
	v_cmp_lt_i32_e32 vcc, 9, v140
	s_nop 1
	v_cndmask_b32_e32 v86, v235, v86, vcc
	v_cmp_lt_i32_e32 vcc, 10, v140
	s_nop 1
	v_cndmask_b32_e32 v87, v235, v87, vcc
	v_cmp_lt_i32_e32 vcc, 15, v140
	s_nop 1
	v_cndmask_b32_e32 v88, v235, v88, vcc
	v_cmp_lt_i32_e32 vcc, 16, v140
	s_nop 1
	v_cndmask_b32_e32 v89, v235, v89, vcc
	v_cmp_lt_i32_e32 vcc, 17, v140
	s_nop 1
	v_cndmask_b32_e32 v90, v235, v90, vcc
	v_cmp_lt_i32_e32 vcc, 18, v140
	s_nop 1
	v_cndmask_b32_e32 v91, v235, v91, vcc
	v_cmp_lt_i32_e32 vcc, 23, v140
	s_nop 1
	v_cndmask_b32_e32 v92, v235, v92, vcc
	v_cmp_lt_i32_e32 vcc, 24, v140
	s_nop 1
	v_cndmask_b32_e32 v93, v235, v93, vcc
	v_cmp_lt_i32_e32 vcc, 25, v140
	s_nop 1
	v_cndmask_b32_e32 v94, v235, v94, vcc
	v_cmp_lt_i32_e32 vcc, 26, v140
	s_nop 1
	v_cndmask_b32_e32 v95, v235, v95, vcc
	v_cmp_lt_i32_e32 vcc, 31, v140
	s_nop 1
	v_cndmask_b32_e32 v64, v235, v64, vcc
	v_cmp_lt_i32_e32 vcc, 32, v140
	s_nop 1
	v_cndmask_b32_e32 v65, v235, v65, vcc
	v_cmp_lt_i32_e32 vcc, 33, v140
	s_nop 1
	v_cndmask_b32_e32 v66, v235, v66, vcc
	v_cmp_lt_i32_e32 vcc, 34, v140
	s_nop 1
	v_cndmask_b32_e32 v67, v235, v67, vcc
	v_cmp_lt_i32_e32 vcc, 39, v140
	s_nop 1
	v_cndmask_b32_e32 v68, v235, v68, vcc
	v_cmp_lt_i32_e32 vcc, 40, v140
	s_nop 1
	v_cndmask_b32_e32 v69, v235, v69, vcc
	v_cmp_lt_i32_e32 vcc, 41, v140
	s_nop 1
	v_cndmask_b32_e32 v70, v235, v70, vcc
	v_cmp_lt_i32_e32 vcc, 42, v140
	s_nop 1
	v_cndmask_b32_e32 v71, v235, v71, vcc
	v_cmp_lt_i32_e32 vcc, 47, v140
	s_nop 1
	v_cndmask_b32_e32 v72, v235, v72, vcc
	v_cmp_lt_i32_e32 vcc, 48, v140
	s_nop 1
	v_cndmask_b32_e32 v73, v235, v73, vcc
	v_cmp_lt_i32_e32 vcc, 49, v140
	s_nop 1
	v_cndmask_b32_e32 v74, v235, v74, vcc
	v_cmp_lt_i32_e32 vcc, 50, v140
	s_nop 1
	v_cndmask_b32_e32 v75, v235, v75, vcc
	v_cmp_lt_i32_e32 vcc, 55, v140
	s_nop 1
	v_cndmask_b32_e32 v76, v235, v76, vcc
	v_cmp_lt_i32_e32 vcc, 56, v140
	s_nop 1
	v_cndmask_b32_e32 v77, v235, v77, vcc
	v_cmp_lt_i32_e32 vcc, 57, v140
	s_nop 1
	v_cndmask_b32_e32 v78, v235, v78, vcc
	v_cmp_lt_i32_e32 vcc, 58, v140
	s_nop 1
	v_cndmask_b32_e32 v79, v235, v79, vcc

.LBB0_88:
	v_exp_f32_e32 v170, v80
	v_exp_f32_e32 v81, v81
	v_exp_f32_e32 v172, v69
	v_exp_f32_e32 v82, v82
	v_exp_f32_e32 v173, v70
	v_exp_f32_e32 v83, v83
	v_exp_f32_e32 v71, v71
	v_add_f32_e32 v80, 0, v170
	v_exp_f32_e32 v84, v84
	v_exp_f32_e32 v174, v72
	v_add_f32_e32 v80, v81, v80
	v_exp_f32_e32 v85, v85
	v_exp_f32_e32 v175, v73
	v_add_f32_e32 v80, v82, v80
	v_exp_f32_e32 v86, v86
	v_exp_f32_e32 v87, v87
	v_exp_f32_e32 v176, v74
	v_add_f32_e32 v80, v83, v80
	v_exp_f32_e32 v177, v75
	v_add_f32_e32 v80, v84, v80
	v_exp_f32_e32 v178, v76
	v_cvt_pk_bf16_f32 v76, v170, v81
	v_add_f32_e32 v80, v85, v80
	v_exp_f32_e32 v179, v77
	v_add_f32_e32 v80, v86, v80
	v_exp_f32_e32 v180, v78
	v_mov_b32_e32 v69, v79
	v_cvt_pk_bf16_f32 v79, v86, v87
	v_cvt_pk_bf16_f32 v77, v82, v83
	v_cvt_pk_bf16_f32 v78, v84, v85
	v_add_f32_e32 v80, v87, v80
	v_exp_f32_e32 v88, v88
	v_exp_f32_e32 v89, v89
	s_waitcnt lgkmcnt(6)
	v_mfma_f32_32x32x16_bf16 v[48:63], v[188:191], v[76:79], v[48:63]
	ds_read_b64_tr_b16 v[188:189], v96 offset:53248
	ds_read_b64_tr_b16 v[190:191], v96 offset:55296
	v_add_f32_e32 v80, v88, v80
	v_cvt_pk_bf16_f32 v72, v88, v89
	v_exp_f32_e32 v90, v90
	s_waitcnt lgkmcnt(6)
	v_mfma_f32_32x32x16_bf16 v[32:47], v[192:195], v[76:79], v[32:47]
	ds_read_b64_tr_b16 v[192:193], v132 offset:53248
	ds_read_b64_tr_b16 v[194:195], v132 offset:55296
	v_exp_f32_e32 v91, v91
	s_waitcnt lgkmcnt(6)
	v_mfma_f32_32x32x16_bf16 v[16:31], v[198:201], v[76:79], v[16:31]
	ds_read_b64_tr_b16 v[198:199], v134 offset:53248
	ds_read_b64_tr_b16 v[200:201], v134 offset:55296
	v_exp_f32_e32 v92, v92
	v_exp_f32_e32 v93, v93
	v_exp_f32_e32 v94, v94
	v_exp_f32_e32 v95, v95
	v_add_f32_e32 v80, v89, v80
	v_add_f32_e32 v80, v90, v80
	s_waitcnt lgkmcnt(6)
	v_mfma_f32_32x32x16_bf16 v[0:15], v[202:205], v[76:79], v[0:15]
	ds_read_b64_tr_b16 v[202:203], v135 offset:53248
	ds_read_b64_tr_b16 v[204:205], v135 offset:55296
	v_add_f32_e32 v80, v91, v80
	v_cvt_pk_bf16_f32 v73, v90, v91
	v_cvt_pk_bf16_f32 v74, v92, v93
	v_cvt_pk_bf16_f32 v75, v94, v95
	v_add_f32_e32 v80, v92, v80
	v_exp_f32_e32 v64, v64
	s_waitcnt lgkmcnt(6)
	v_mfma_f32_32x32x16_bf16 v[48:63], v[188:191], v[72:75], v[48:63]
	ds_read_b64_tr_b16 v[188:189], v96 offset:57344
	ds_read_b64_tr_b16 v[190:191], v96 offset:59392
	v_add_f32_e32 v80, v93, v80
	v_exp_f32_e32 v65, v65
	v_add_f32_e32 v80, v94, v80
	v_exp_f32_e32 v66, v66
	v_add_f32_e32 v80, v95, v80
	v_exp_f32_e32 v67, v67
	v_add_f32_e32 v80, v64, v80
	v_exp_f32_e32 v171, v68
	v_add_f32_e32 v80, v65, v80
	s_waitcnt lgkmcnt(6)
	v_mfma_f32_32x32x16_bf16 v[32:47], v[192:195], v[72:75], v[32:47]
	ds_read_b64_tr_b16 v[192:193], v132 offset:57344
	ds_read_b64_tr_b16 v[194:195], v132 offset:59392
	v_add_f32_e32 v80, v66, v80
	v_add_f32_e32 v80, v67, v80
	v_add_f32_e32 v68, v171, v80
	v_add_f32_e32 v68, v172, v68
	v_add_f32_e32 v68, v173, v68
	v_add_f32_e32 v68, v71, v68
	s_waitcnt lgkmcnt(6)
	v_mfma_f32_32x32x16_bf16 v[16:31], v[198:201], v[72:75], v[16:31]
	ds_read_b64_tr_b16 v[198:199], v134 offset:57344
	ds_read_b64_tr_b16 v[200:201], v134 offset:59392
	v_add_f32_e32 v68, v174, v68
	v_add_f32_e32 v68, v175, v68
	v_add_f32_e32 v68, v176, v68
	v_add_f32_e32 v68, v177, v68
	v_exp_f32_e32 v181, v69
	v_add_f32_e32 v68, v178, v68
	s_waitcnt lgkmcnt(6)
	v_mfma_f32_32x32x16_bf16 v[0:15], v[202:205], v[72:75], v[0:15]
	ds_read_b64_tr_b16 v[202:203], v135 offset:57344
	ds_read_b64_tr_b16 v[204:205], v135 offset:59392
	v_add_f32_e32 v68, v179, v68
	v_add_f32_e32 v68, v180, v68
	v_add_f32_e32 v80, v181, v68
	v_cvt_pk_bf16_f32 v68, v64, v65
	v_cvt_pk_bf16_f32 v69, v66, v67
	v_cvt_pk_bf16_f32 v70, v171, v172
	v_cvt_pk_bf16_f32 v71, v173, v71
	v_cvt_pk_bf16_f32 v64, v174, v175
	v_cvt_pk_bf16_f32 v65, v176, v177
	s_waitcnt lgkmcnt(6)
	v_mfma_f32_32x32x16_bf16 v[48:63], v[188:191], v[68:71], v[48:63]
	ds_read_b64_tr_b16 v[188:189], v96 offset:61440
	ds_read_b64_tr_b16 v[190:191], v96 offset:63488
	v_cvt_pk_bf16_f32 v66, v178, v179
	v_cvt_pk_bf16_f32 v67, v180, v181
	v_add_f32_e32 v168, v168, v80
	s_waitcnt lgkmcnt(6)
	v_mfma_f32_32x32x16_bf16 v[32:47], v[192:195], v[68:71], v[32:47]
	ds_read_b64_tr_b16 v[192:193], v132 offset:61440
	ds_read_b64_tr_b16 v[194:195], v132 offset:63488
	s_waitcnt lgkmcnt(6)
	v_mfma_f32_32x32x16_bf16 v[16:31], v[198:201], v[68:71], v[16:31]
	ds_read_b64_tr_b16 v[198:199], v134 offset:61440
	ds_read_b64_tr_b16 v[200:201], v134 offset:63488
	s_waitcnt lgkmcnt(6)
	v_mfma_f32_32x32x16_bf16 v[0:15], v[202:205], v[68:71], v[0:15]
	ds_read_b64_tr_b16 v[202:203], v135 offset:61440
	ds_read_b64_tr_b16 v[204:205], v135 offset:63488
	s_waitcnt lgkmcnt(6)
	v_mfma_f32_32x32x16_bf16 v[48:63], v[188:191], v[64:67], v[48:63]
	s_waitcnt lgkmcnt(4)
	v_mfma_f32_32x32x16_bf16 v[32:47], v[192:195], v[64:67], v[32:47]
	s_waitcnt lgkmcnt(2)
	v_mfma_f32_32x32x16_bf16 v[16:31], v[198:201], v[64:67], v[16:31]
	s_waitcnt lgkmcnt(0)
	v_mfma_f32_32x32x16_bf16 v[0:15], v[202:205], v[64:67], v[0:15]
